# static priority raise (s_setprio 1) for waves 4-7 during the stick-breaking attention phase, reset at phase end
# speedup vs baseline: 1.0054x; 1.0054x over previous
; __device__ __forceinline__ void sb_item(const bf16_t* hbuf, const float* kmax2, bf16_t* mixed, LAS bf16_t* vT, int item, int lane) {
;     ...
;                 const int m = 16 * mt + r; unsigned tw[4];
; #pragma unroll
;                 for (int p = 0; p < 4; ++p) { const int i0 = 2 * p, i1 = 2 * p + 1;
;                     const int ma = 32 * mb + (i0 < 4 ? 4 * q + i0 : 16 + 4 * q + i0 - 4), mbb = 32 * mb + (i1 < 4 ? 4 * q + i1 : 16 + 4 * q + i1 - 4);
;                     tw[p] = (ma >= m ? 0x3f80u : 0u) | (mbb >= m ? 0x3f800000u : 0u); }
;                 const bf16x8 tri = as_bf16x8((u32x4){tw[0], tw[1], tw[2], tw[3]});
; __device__ __forceinline__ void run_phase(const Args& a, const int ph, LAS unsigned char* lds, const int tid, const int rpt) {
;     ...
;                   if (rpt == 0) {
;                       const int nstat = (4 * NGW <= 12 * 1024) ? 4 * NGW : 0;
;                       if (nstat) for (int it = 4 * gw; it < 4 * gw + 4; ++it) sb_item(hbuf, kmax2, mixed, vT, it, lane);
.LBB0_230:
.LBB0_231:
	v_readlane_b32 s1, v249, 49
	s_lshl_b32 s0, s1, 5
	s_cmpk_lt_i32 s1, 0x181
	s_cselect_b32 s0, s0, 0
	s_cmp_lg_u32 s0, 0
	v_writelane_b32 v249, s0, 54
	s_cbranch_scc0 .LBB0_552
	v_readlane_b32 s98, v249, 52
	s_nop 0
	s_cmp_gt_u32 s98, 3
	s_cbranch_scc0 .Lsbp_skip
	s_setprio 1
.Lsbp_skip:
	v_lshrrev_b32_e32 v0, 4, v248
	v_and_b32_e32 v122, 15, v168
	v_lshlrev_b32_e32 v120, 2, v0
	v_lshlrev_b32_e32 v1, 2, v248
	v_or_b32_e32 v143, 1, v120
	v_cmp_lt_u32_e32 vcc, v120, v122
	v_mov_b32_e32 v7, 0x3f80
	v_lshlrev_b32_e32 v124, 3, v0
	v_xor_b32_e32 v132, 64, v1
	v_xor_b32_e32 v133, 0x80, v1
	v_and_b32_e32 v1, 7, v168
	v_cndmask_b32_e64 v0, v7, 0, vcc
	v_cmp_lt_u32_e32 vcc, v143, v122
	v_or_b32_e32 v144, 2, v120
	v_lshrrev_b32_e32 v134, 3, v248
	v_lshlrev_b32_e32 v126, 3, v1
	v_mul_u32_u24_e32 v139, 0x440, v1
	v_cndmask_b32_e64 v1, 1.0, 0, vcc
	v_or_b32_e32 v145, 3, v120
	v_cmp_lt_u32_e32 vcc, v144, v122
	v_lshlrev_b32_e32 v2, 1, v134
	v_readlane_b32 s0, v249, 53
	v_or_b32_e32 v36, v1, v0
	v_cndmask_b32_e64 v1, v7, 0, vcc
	v_cmp_lt_u32_e32 vcc, v145, v122
	v_or_b32_e32 v140, 17, v120
	v_or_b32_e32 v146, 16, v122
	v_add3_u32 v151, s0, v2, v139
	v_cndmask_b32_e64 v2, 1.0, 0, vcc
	v_or_b32_e32 v141, 18, v120
	v_cmp_lt_u32_e32 vcc, v140, v146
	v_or_b32_e32 v37, v2, v1
	v_or_b32_e32 v142, 19, v120
	v_cndmask_b32_e64 v1, 1.0, 0, vcc
	v_cmp_lt_u32_e32 vcc, v141, v146
	v_or_b32_e32 v8, 48, v248
	v_or_b32_e32 v136, 16, v120
	v_or_b32_e32 v2, v1, v0
	v_cndmask_b32_e64 v0, v7, 0, vcc
	v_cmp_lt_u32_e32 vcc, v142, v146
	v_subrev_u32_e32 v147, 32, v8
	s_lshl_b32 s12, s16, 2
	v_cndmask_b32_e64 v1, 1.0, 0, vcc
	v_cmp_lt_u32_e32 vcc, v136, v147
	v_add_u32_e32 v152, s0, v124
	s_movk_i32 s0, 0x88
	v_cndmask_b32_e64 v4, v7, 0, vcc
	v_cmp_lt_u32_e32 vcc, v140, v147
	s_waitcnt vmcnt(0)
	v_mov_b32_e32 v9, 0x880
	v_mov_b32_e32 v123, v33
	v_cndmask_b32_e64 v5, 1.0, 0, vcc
	v_cmp_lt_u32_e32 vcc, v141, v147
	v_or_b32_e32 v6, v5, v4
	v_mov_b32_e32 v125, v33
	v_cndmask_b32_e64 v4, v7, 0, vcc
	v_cmp_lt_u32_e32 vcc, v142, v147
	v_mov_b32_e32 v127, v33
	v_lshlrev_b32_e32 v135, 2, v122
	v_cndmask_b32_e64 v5, 1.0, 0, vcc
	v_mov_b32_e32 v39, v38
	v_or_b32_e32 v3, v1, v0
	v_mov_b32_e32 v0, v33
	v_mov_b32_e32 v1, v33
	v_or_b32_e32 v7, v5, v4
	v_mov_b32_e32 v4, v33
	v_mov_b32_e32 v5, v33
	v_mul_u32_u24_e32 v148, 0x88, v122
	v_mad_u32_u24 v149, v122, s0, v9
	v_mul_u32_u24_e32 v150, 0x88, v8
	v_or_b32_e32 v137, 32, v120
	v_or_b32_e32 v138, 48, v120
	v_mov_b32_e32 v121, v33
	s_or_b32 s15, s12, 3
	s_branch .LBB0_234

; #define LAS __attribute__((address_space(3)))
; __device__ __forceinline__ void run_phase(const Args& a, const int ph, LAS unsigned char* lds, const int tid, const int rpt) {
;     ...
;                 { unsigned* qctr = (unsigned*)(ws + WS_BAR) + l * 16;
;                   LAS bf16_t* vT = (LAS bf16_t*)(lds + wave * 9216);
;                   if (rpt == 0) {
;                       const int nstat = (4 * NGW <= 12 * 1024) ? 4 * NGW : 0;
;                       if (nstat) for (int it = 4 * gw; it < 4 * gw + 4; ++it) sb_item(hbuf, kmax2, mixed, vT, it, lane);
;                       for (;;) { int it0 = 0; if (lane == 0) it0 = (int)atomicAdd(qctr, 2u); it0 = nstat + __builtin_amdgcn_readfirstlane(it0); if (it0 >= 12 * 1024) break;
;                           for (int it = it0; it < it0 + 2; ++it) sb_item(hbuf, kmax2, mixed, vT, it, lane); } }
;                   else { for (int it = gw; it < 12 * 1024; it += NGW) sb_item(hbuf, kmax2, mixed, vT, it, lane); } }
.LBB0_321:
	s_setprio 0
	s_mov_b64 s[0:1], 0
